# input rows for the first RMSNorm phase are loaded by waves 1-7 before the first grid barrier (cross-barrier prefetch of kernel inputs)
# baseline (speedup 1.0000x reference)
; __device__ __forceinline__ void norm_mod_phase(const float* X, const float* ng, const float* mod, bf16* H, int G) {
;     ...
;         for (int tb = gw; tb < SEQL; tb += 4 * NGW) {
;             f32x4 v[4][4]; float s[4]; int mr[4]; bool has[4];
; #pragma unroll
;             for (int r = 0; r < 4; ++r) { const int t = tb + r * NGW; has[r] = t < SEQL; mr[r] = b * SEQL + (has[r] ? t : tb); const f32x4* xr = (const f32x4*)(X + (size_t)mr[r] * D) + lane;
; #pragma unroll
;                 for (int j = 0; j < 4; ++j) v[r][j] = xr[64 * j]; }
; __device__ __forceinline__ void xcd_barrier(const XcdBarrier& b) {
;     asm volatile("s_waitcnt vmcnt(0)" ::: "memory");
;     __syncthreads();
;     if (threadIdx.x == 0) {
.LBB0_33:
	s_or_b64 exec, exec, s[14:15]
	s_add_u32 s94, s10, 0x4200
	s_addc_u32 s95, s11, 0
	s_add_u32 s14, s10, 0x4400
	s_addc_u32 s15, s11, 0
	v_writelane_b32 v249, s14, 5
	s_mul_i32 s5, s7, s6
	s_mul_i32 s30, s5, s3
	v_writelane_b32 v249, s15, 6
	s_add_u32 s14, s10, 0x4500
	s_addc_u32 s15, s11, 0
	v_writelane_b32 v249, s14, 7
	s_waitcnt vmcnt(0)
	s_barrier
	s_mov_b32 s32, 0
	s_cmp_eq_u32 s6, 0x100
	s_cbranch_scc0 .Lpfx_skip
	v_readfirstlane_b32 s98, v216
	s_lshr_b32 s98, s98, 6
	s_cmp_eq_u32 s98, 0
	s_cbranch_scc1 .Lpfx_skip
	v_readlane_b32 s99, v249, 2
	s_lshl_b32 s99, s99, 3
	s_add_i32 s98, s99, s98
	v_and_b32_e32 v255, 63, v216
	v_lshlrev_b32_e32 v255, 4, v255
	s_mov_b32 s99, s98
	s_lshl_b32 s100, s99, 12
	s_add_u32 s100, s68, s100
	s_addc_u32 s101, s69, 0
	global_load_dwordx4 v[116:119], v255, s[100:101]
	global_load_dwordx4 v[120:123], v255, s[100:101] offset:1024
	global_load_dwordx4 v[124:127], v255, s[100:101] offset:2048
	global_load_dwordx4 v[128:131], v255, s[100:101] offset:3072
	s_addk_i32 s99, 0x800
	s_lshl_b32 s100, s99, 12
	s_add_u32 s100, s68, s100
	s_addc_u32 s101, s69, 0
	global_load_dwordx4 v[132:135], v255, s[100:101]
	global_load_dwordx4 v[136:139], v255, s[100:101] offset:1024
	global_load_dwordx4 v[140:143], v255, s[100:101] offset:2048
	global_load_dwordx4 v[144:147], v255, s[100:101] offset:3072
	s_addk_i32 s99, 0x800
	s_lshl_b32 s100, s99, 12
	s_add_u32 s100, s68, s100
	s_addc_u32 s101, s69, 0
	global_load_dwordx4 v[148:151], v255, s[100:101]
	global_load_dwordx4 v[152:155], v255, s[100:101] offset:1024
	global_load_dwordx4 v[156:159], v255, s[100:101] offset:2048
	global_load_dwordx4 v[160:163], v255, s[100:101] offset:3072
	s_addk_i32 s99, 0x800
	s_lshl_b32 s100, s99, 12
	s_add_u32 s100, s68, s100
	s_addc_u32 s101, s69, 0
	global_load_dwordx4 v[164:167], v255, s[100:101]
	global_load_dwordx4 v[168:171], v255, s[100:101] offset:1024
	global_load_dwordx4 v[172:175], v255, s[100:101] offset:2048
	global_load_dwordx4 v[176:179], v255, s[100:101] offset:3072
	s_add_i32 s99, s98, 8192
	s_lshl_b32 s100, s99, 12
	s_add_u32 s100, s68, s100
	s_addc_u32 s101, s69, 0
	global_load_dwordx4 v[180:183], v255, s[100:101]
	global_load_dwordx4 v[184:187], v255, s[100:101] offset:1024
	global_load_dwordx4 v[188:191], v255, s[100:101] offset:2048
	global_load_dwordx4 v[192:195], v255, s[100:101] offset:3072
	s_addk_i32 s99, 0x800
	s_lshl_b32 s100, s99, 12
	s_add_u32 s100, s68, s100
	s_addc_u32 s101, s69, 0
	global_load_dwordx4 v[86:89], v255, s[100:101]
	global_load_dwordx4 v[90:93], v255, s[100:101] offset:1024
	global_load_dwordx4 v[94:97], v255, s[100:101] offset:2048
	global_load_dwordx4 v[98:101], v255, s[100:101] offset:3072
	s_addk_i32 s99, 0x800
	s_lshl_b32 s100, s99, 12
	s_add_u32 s100, s68, s100
	s_addc_u32 s101, s69, 0
	global_load_dwordx4 v[218:221], v255, s[100:101]
	global_load_dwordx4 v[222:225], v255, s[100:101] offset:1024
	global_load_dwordx4 v[226:229], v255, s[100:101] offset:2048
	global_load_dwordx4 v[230:233], v255, s[100:101] offset:3072
	s_addk_i32 s99, 0x800
	s_lshl_b32 s100, s99, 12
	s_add_u32 s100, s68, s100
	s_addc_u32 s101, s69, 0
	global_load_dwordx4 v[196:199], v255, s[100:101]
	global_load_dwordx4 v[200:203], v255, s[100:101] offset:1024
	global_load_dwordx4 v[204:207], v255, s[100:101] offset:2048
	global_load_dwordx4 v[102:105], v255, s[100:101] offset:3072
	s_mov_b32 s32, 1
; __device__ __forceinline__ unsigned xb_ld(unsigned* p)              { return __hip_atomic_load(p, __ATOMIC_RELAXED, __HIP_MEMORY_SCOPE_AGENT); }
; __device__ __forceinline__ void xcd_barrier_complete(unsigned* bar, unsigned x, unsigned& nloc, unsigned& nx) {
;     const unsigned G = gridDim.x * gridDim.y * gridDim.z;
;     unsigned sum, cnt, mine, sp = 0u;
;     for (;;) {
;         sum = 0u; cnt = 0u; mine = 0u;
; #pragma unroll
;         for (unsigned j = 0; j < 16; ++j) { const unsigned c = xb_ld(&bar[XB_XCNT(j)]); sum += c; cnt += (c > 0u) ? 1u : 0u; mine = (j == x) ? c : mine; }
;         if (sum == G) break;
;         __builtin_amdgcn_s_sleep(1);
;         if ((++sp & 255u) == 0u) { if (xb_ld(&bar[XB_TMO])) break; if (sp > XB_SPIN_CAP) { atomicAdd(&bar[XB_TMO], 1u); break; } }
;     }
;     nloc = mine > 0u ? mine : 1u; nx = cnt > 0u ? cnt : 1u;
; }
; __device__ __forceinline__ void xcd_barrier(const XcdBarrier& b) {
;     asm volatile("s_waitcnt vmcnt(0)" ::: "memory");
;     __syncthreads();
;     if (threadIdx.x == 0) {
;         unsigned* bar = b.bar;
;         __builtin_amdgcn_s_waitcnt(0);
;         unsigned nloc = b.st[0], nx = b.st[1];
;         if (nloc == 0u) { xcd_barrier_complete(bar, b.x, nloc, nx); b.st[0] = nloc; b.st[1] = nx; }
.Lpfx_skip:
	s_nop 0
	v_writelane_b32 v249, s15, 8
	s_add_u32 s14, s10, 0x4600
	s_addc_u32 s15, s11, 0
	v_writelane_b32 v249, s14, 9
	s_nop 1
	v_writelane_b32 v249, s15, 10
	s_add_u32 s14, s10, 0x4700
	s_addc_u32 s15, s11, 0
	v_writelane_b32 v249, s14, 11
	s_nop 1
	v_writelane_b32 v249, s15, 12
	s_add_u32 s14, s10, 0x4800
	s_addc_u32 s15, s11, 0
	v_writelane_b32 v249, s14, 13
	s_nop 1
	v_writelane_b32 v249, s15, 14
	s_add_u32 s14, s10, 0x4900
	s_addc_u32 s15, s11, 0
	v_writelane_b32 v249, s14, 15
	s_nop 1
	v_writelane_b32 v249, s15, 16
	s_add_u32 s14, s10, 0x4a00
	s_addc_u32 s15, s11, 0
	v_writelane_b32 v249, s14, 17
	s_nop 1
	v_writelane_b32 v249, s15, 18
	s_add_u32 s14, s10, 0x4b00
	s_addc_u32 s15, s11, 0
	v_writelane_b32 v249, s14, 19
	s_nop 1
	v_writelane_b32 v249, s15, 20
	s_add_u32 s14, s10, 0x4c00
	s_addc_u32 s15, s11, 0
	v_writelane_b32 v249, s14, 21
	s_nop 1
	v_writelane_b32 v249, s15, 22
	s_add_u32 s14, s10, 0x4d00
	s_addc_u32 s15, s11, 0
	v_writelane_b32 v249, s14, 23
	s_nop 1
	v_writelane_b32 v249, s15, 24
	s_add_u32 s14, s10, 0x4e00
	s_addc_u32 s15, s11, 0
	v_writelane_b32 v249, s14, 25
	s_nop 1
	v_writelane_b32 v249, s15, 26
	s_add_u32 s14, s10, 0x4f00
	s_addc_u32 s15, s11, 0
	v_writelane_b32 v249, s14, 27
	s_nop 1
	v_writelane_b32 v249, s15, 28
	s_add_u32 s14, s10, 0x5000
	s_addc_u32 s15, s11, 0
	v_writelane_b32 v249, s14, 29
	s_nop 1
	v_writelane_b32 v249, s15, 30
	s_add_u32 s14, s10, 0x5100
	s_addc_u32 s15, s11, 0
	v_writelane_b32 v249, s14, 31
	s_nop 1
	v_writelane_b32 v249, s15, 32
	s_add_u32 s14, s10, 0x5200
	s_addc_u32 s15, s11, 0
	s_add_u32 s34, s10, 0x5300
	s_addc_u32 s35, s11, 0
	v_writelane_b32 v249, s14, 33
	s_cmp_eq_u32 s22, 15
	s_nop 0
	v_writelane_b32 v249, s15, 34
	s_cselect_b64 s[14:15], -1, 0
	v_writelane_b32 v249, s14, 35
	s_cmp_eq_u32 s22, 14
	s_nop 0
	v_writelane_b32 v249, s15, 36
	s_cselect_b64 s[14:15], -1, 0
	v_writelane_b32 v249, s14, 37
	s_cmp_eq_u32 s22, 13
	s_nop 0
	v_writelane_b32 v249, s15, 38
	s_cselect_b64 s[14:15], -1, 0
	v_writelane_b32 v249, s14, 39
	s_cmp_eq_u32 s22, 12
	s_nop 0
	v_writelane_b32 v249, s15, 40
	s_cselect_b64 s[14:15], -1, 0
	v_writelane_b32 v249, s14, 41
	s_cmp_eq_u32 s22, 11
	s_nop 0
	v_writelane_b32 v249, s15, 42
	s_cselect_b64 s[14:15], -1, 0
	v_writelane_b32 v249, s14, 43
	s_cmp_eq_u32 s22, 10
	s_nop 0
	v_writelane_b32 v249, s15, 44
	s_cselect_b64 s[14:15], -1, 0
	v_writelane_b32 v249, s14, 45
	s_cmp_eq_u32 s22, 9
	s_nop 0
	v_writelane_b32 v249, s15, 46
	s_cselect_b64 s[14:15], -1, 0
	v_writelane_b32 v249, s14, 47
	s_cmp_eq_u32 s22, 8
	s_nop 0
	v_writelane_b32 v249, s15, 48
	s_cselect_b64 s[14:15], -1, 0
	v_writelane_b32 v249, s14, 49
	s_cmp_eq_u32 s22, 7
	s_nop 0
	v_writelane_b32 v249, s15, 50
	s_cselect_b64 s[14:15], -1, 0
	v_writelane_b32 v249, s14, 51
	s_cmp_eq_u32 s22, 6
	s_nop 0
	v_writelane_b32 v249, s15, 52
	s_cselect_b64 s[14:15], -1, 0
	v_writelane_b32 v249, s14, 53
	s_cmp_eq_u32 s22, 5
	s_nop 0
	v_writelane_b32 v249, s15, 54
	s_cselect_b64 s[14:15], -1, 0
	v_writelane_b32 v249, s14, 55
	s_cmp_eq_u32 s22, 4
	s_nop 0
	v_writelane_b32 v249, s15, 56
	s_cselect_b64 s[14:15], -1, 0
	v_writelane_b32 v249, s14, 57
	s_cmp_eq_u32 s22, 3
	s_nop 0
	v_writelane_b32 v249, s15, 58
	s_cselect_b64 s[14:15], -1, 0
	v_writelane_b32 v249, s14, 59
	s_cmp_eq_u32 s22, 2
	s_nop 0
	v_writelane_b32 v249, s15, 60
	s_cselect_b64 s[14:15], -1, 0
	v_writelane_b32 v249, s14, 61
	s_cmp_eq_u32 s22, 1
	s_nop 0
	v_writelane_b32 v249, s15, 62
	s_cselect_b64 s[14:15], -1, 0
	v_writelane_b32 v249, s14, 63
	s_cmp_eq_u32 s22, 0
	s_nop 0
	v_writelane_b32 v248, s15, 0
	s_cselect_b64 s[14:15], -1, 0
	s_lshl_b32 s3, s23, 2
	s_add_u32 s3, s12, s3
	s_addc_u32 s5, s13, 0
	s_add_u32 s28, s3, 0x1400
	s_addc_u32 s29, s5, 0
	s_add_u32 s96, s3, 0x2400
	s_addc_u32 s97, s5, 0
	s_add_u32 s12, s10, 0x7400
	v_writelane_b32 v248, s14, 1
	s_addc_u32 s13, s11, 0
	s_add_u32 s26, s10, 0x7500
	v_writelane_b32 v248, s15, 2
	v_writelane_b32 v248, s12, 3
	s_addc_u32 s27, s11, 0
	s_nop 0
	v_writelane_b32 v248, s13, 4
	s_and_saveexec_b64 s[12:13], s[92:93]
	s_cbranch_execz .LBB0_85
	s_add_i32 s3, 0, 0x23fc0
	v_mov_b32_e32 v0, s3
	s_waitcnt vmcnt(0) expcnt(0) lgkmcnt(0)
	ds_read_b32 v2, v0
	s_add_i32 s3, 0, 0x23fc4
	v_mov_b32_e32 v0, s3
	ds_read_b32 v0, v0
	s_waitcnt lgkmcnt(1)
	v_cmp_ne_u32_e32 vcc, 0, v2
	s_cbranch_vccnz .LBB0_49
	s_mov_b32 s3, 1
	v_mov_b32_e32 v16, 0
	s_branch .LBB0_37

; __device__ __forceinline__ void norm_mod_phase(const float* X, const float* ng, const float* mod, bf16* H, int G) {
;     int tid = threadIdx.x; asm volatile("" : "+v"(tid)); const int lane = tid & 63, wave = tid >> 6;
;     const int gw = blockIdx.x * NWAVES + wave, NGW = G * NWAVES;
; #pragma unroll 1
;     for (int b = 0; b < 2; ++b) {
;         f32x4 gs[4], sh[4];
; #pragma unroll
;         for (int j = 0; j < 4; ++j) { const int c = 4 * lane + 256 * j; gs[j] = *(const f32x4*)(ng + c) * (*(const f32x4*)(mod + b * 3072 + 1024 + c) + 1.0f); sh[j] = *(const f32x4*)(mod + b * 3072 + c); }
;         for (int tb = gw; tb < SEQL; tb += 4 * NGW) {
;             f32x4 v[4][4]; float s[4]; int mr[4]; bool has[4];
; #pragma unroll
;             for (int r = 0; r < 4; ++r) { const int t = tb + r * NGW; has[r] = t < SEQL; mr[r] = b * SEQL + (has[r] ? t : tb); const f32x4* xr = (const f32x4*)(X + (size_t)mr[r] * D) + lane;
; #pragma unroll
;                 for (int j = 0; j < 4; ++j) v[r][j] = xr[64 * j]; }
.LBB0_85:
	s_or_b64 exec, exec, s[12:13]
	s_waitcnt lgkmcnt(0)
	v_mov_b32_e32 v0, v216
	s_barrier
	s_add_u32 s12, s10, 0x1800000
	v_and_b32_e32 v1, 63, v0
	v_ashrrev_i32_e32 v0, 6, v0
	v_readlane_b32 s3, v249, 3
	v_mov_b32_e32 v3, 0
	s_addc_u32 s13, s11, 0
	v_add_u32_e32 v110, s3, v0
	v_lshlrev_b32_e32 v0, 2, v1
	v_lshlrev_b32_e32 v2, 4, v1
	v_lshlrev_b32_e32 v4, 3, v1
	v_mov_b32_e32 v5, v3
	v_lshl_add_u64 v[80:81], s[68:69], 0, v[2:3]
	v_lshl_add_u64 v[82:83], s[12:13], 0, v[4:5]
	v_lshl_add_u64 v[84:85], s[72:73], 0, v[2:3]
	v_or_b32_e32 v2, 0x100, v0
	v_or_b32_e32 v4, 0x200, v0
	v_or_b32_e32 v6, 0x300, v0
	v_lshlrev_b32_e32 v111, 2, v0
	v_mbcnt_lo_u32_b32 v0, -1, 0
	v_mbcnt_hi_u32_b32 v208, -1, v0
	s_movk_i32 s3, 0x2000
	s_add_i32 s7, s4, s4
	v_and_b32_e32 v217, 64, v208
	v_cmp_gt_i32_e64 s[36:37], s3, v110
	s_lshl_b32 s5, s6, 4
	s_mov_b32 s21, 0
	s_mov_b64 s[22:23], -1
	v_lshlrev_b32_e32 v112, 2, v2
	v_lshlrev_b32_e32 v113, 2, v4
	v_lshlrev_b32_e32 v114, 2, v6
	v_mov_b32_e32 v115, 0x358637bd
	s_add_i32 s7, s7, s4
	v_add_u32_e32 v209, 64, v217
	v_xor_b32_e32 v215, 1, v208
	v_xor_b32_e32 v214, 2, v208
	v_xor_b32_e32 v213, 4, v208
	v_xor_b32_e32 v212, 8, v208
	v_xor_b32_e32 v211, 16, v208
	v_xor_b32_e32 v210, 32, v208
	s_cmp_eq_u32 s6, 0x100
	s_cbranch_scc0 .Lnorm_orig
	v_lshlrev_b32_e32 v107, 4, v208
	v_lshlrev_b32_e32 v106, 3, v208
	v_readfirstlane_b32 s16, v110
	s_lshl_b32 s14, s6, 3
	s_add_u32 s38, s0, 0x1000
	s_addc_u32 s39, s1, 0
	s_add_u32 s40, s0, 0x3000
	s_addc_u32 s41, s1, 0
	s_add_u32 s42, s0, 0x4000
	s_addc_u32 s43, s1, 0
	global_load_dwordx4 v[0:3], v107, s[72:73]
	global_load_dwordx4 v[4:7], v107, s[72:73] offset:1024
	global_load_dwordx4 v[8:11], v107, s[72:73] offset:2048
	global_load_dwordx4 v[12:15], v107, s[72:73] offset:3072
	global_load_dwordx4 v[16:19], v107, s[38:39]
	global_load_dwordx4 v[20:23], v107, s[38:39] offset:1024
	global_load_dwordx4 v[24:27], v107, s[38:39] offset:2048
	global_load_dwordx4 v[28:31], v107, s[38:39] offset:3072
	global_load_dwordx4 v[32:35], v107, s[0:1]
	global_load_dwordx4 v[36:39], v107, s[0:1] offset:1024
	global_load_dwordx4 v[40:43], v107, s[0:1] offset:2048
	global_load_dwordx4 v[44:47], v107, s[0:1] offset:3072
	global_load_dwordx4 v[48:51], v107, s[42:43]
	global_load_dwordx4 v[52:55], v107, s[42:43] offset:1024
	global_load_dwordx4 v[56:59], v107, s[42:43] offset:2048
	global_load_dwordx4 v[60:63], v107, s[42:43] offset:3072
	global_load_dwordx4 v[64:67], v107, s[40:41]
	global_load_dwordx4 v[68:71], v107, s[40:41] offset:1024
	global_load_dwordx4 v[72:75], v107, s[40:41] offset:2048
	global_load_dwordx4 v[76:79], v107, s[40:41] offset:3072
	s_cmp_eq_u32 s32, 1
	s_cbranch_scc1 .Lnorm_rows_done
	s_mov_b32 s18, s16
	s_lshl_b32 s20, s18, 12
	s_add_u32 s22, s68, s20
	s_addc_u32 s23, s69, 0
	global_load_dwordx4 v[116:119], v107, s[22:23]
	global_load_dwordx4 v[120:123], v107, s[22:23] offset:1024
	global_load_dwordx4 v[124:127], v107, s[22:23] offset:2048
	global_load_dwordx4 v[128:131], v107, s[22:23] offset:3072
	s_add_i32 s18, s18, s14
	s_lshl_b32 s20, s18, 12
	s_add_u32 s22, s68, s20
	s_addc_u32 s23, s69, 0
	global_load_dwordx4 v[132:135], v107, s[22:23]
	global_load_dwordx4 v[136:139], v107, s[22:23] offset:1024
	global_load_dwordx4 v[140:143], v107, s[22:23] offset:2048
	global_load_dwordx4 v[144:147], v107, s[22:23] offset:3072
	s_add_i32 s18, s18, s14
	s_lshl_b32 s20, s18, 12
	s_add_u32 s22, s68, s20
	s_addc_u32 s23, s69, 0
	global_load_dwordx4 v[148:151], v107, s[22:23]
	global_load_dwordx4 v[152:155], v107, s[22:23] offset:1024
	global_load_dwordx4 v[156:159], v107, s[22:23] offset:2048
	global_load_dwordx4 v[160:163], v107, s[22:23] offset:3072
	s_add_i32 s18, s18, s14
	s_lshl_b32 s20, s18, 12
	s_add_u32 s22, s68, s20
	s_addc_u32 s23, s69, 0
	global_load_dwordx4 v[164:167], v107, s[22:23]
	global_load_dwordx4 v[168:171], v107, s[22:23] offset:1024
	global_load_dwordx4 v[172:175], v107, s[22:23] offset:2048
	global_load_dwordx4 v[176:179], v107, s[22:23] offset:3072
	s_add_i32 s18, s16, 8192
	s_lshl_b32 s20, s18, 12
	s_add_u32 s22, s68, s20
	s_addc_u32 s23, s69, 0
	global_load_dwordx4 v[180:183], v107, s[22:23]
	global_load_dwordx4 v[184:187], v107, s[22:23] offset:1024
	global_load_dwordx4 v[188:191], v107, s[22:23] offset:2048
	global_load_dwordx4 v[192:195], v107, s[22:23] offset:3072
	s_add_i32 s18, s18, s14
	s_lshl_b32 s20, s18, 12
	s_add_u32 s22, s68, s20
	s_addc_u32 s23, s69, 0
	global_load_dwordx4 v[86:89], v107, s[22:23]
	global_load_dwordx4 v[90:93], v107, s[22:23] offset:1024
	global_load_dwordx4 v[94:97], v107, s[22:23] offset:2048
	global_load_dwordx4 v[98:101], v107, s[22:23] offset:3072
	s_add_i32 s18, s18, s14
	s_lshl_b32 s20, s18, 12
	s_add_u32 s22, s68, s20
	s_addc_u32 s23, s69, 0
	global_load_dwordx4 v[218:221], v107, s[22:23]
	global_load_dwordx4 v[222:225], v107, s[22:23] offset:1024
	global_load_dwordx4 v[226:229], v107, s[22:23] offset:2048
	global_load_dwordx4 v[230:233], v107, s[22:23] offset:3072
	s_add_i32 s18, s18, s14
	s_lshl_b32 s20, s18, 12
	s_add_u32 s22, s68, s20
	s_addc_u32 s23, s69, 0
	global_load_dwordx4 v[196:199], v107, s[22:23]
	global_load_dwordx4 v[200:203], v107, s[22:23] offset:1024
	global_load_dwordx4 v[204:207], v107, s[22:23] offset:2048
	global_load_dwordx4 v[102:105], v107, s[22:23] offset:3072
.Lnorm_rows_done:
	v_xor_b32_e32 v242, 1, v208
	v_lshlrev_b32_e32 v242, 2, v242
	v_xor_b32_e32 v243, 2, v208
	v_lshlrev_b32_e32 v243, 2, v243
	v_xor_b32_e32 v244, 4, v208
	v_lshlrev_b32_e32 v244, 2, v244
	v_xor_b32_e32 v245, 8, v208
	v_lshlrev_b32_e32 v245, 2, v245
	v_xor_b32_e32 v246, 16, v208
	v_lshlrev_b32_e32 v246, 2, v246
	v_xor_b32_e32 v247, 32, v208
	v_lshlrev_b32_e32 v247, 2, v247
	v_mov_b32_e32 v108, 0x358637bd
	s_cmp_eq_u32 s32, 1
	s_cbranch_scc0 .Lnorm_w32
	s_waitcnt vmcnt(0)
; __device__ __forceinline__ void norm_mod_phase(const float* X, const float* ng, const float* mod, bf16* H, int G) {
;     ...
;         for (int j = 0; j < 4; ++j) { const int c = 4 * lane + 256 * j; gs[j] = *(const f32x4*)(ng + c) * (*(const f32x4*)(mod + b * 3072 + 1024 + c) + 1.0f); sh[j] = *(const f32x4*)(mod + b * 3072 + c); }
;         for (int tb = gw; tb < SEQL; tb += 4 * NGW) {
;             f32x4 v[4][4]; float s[4]; int mr[4]; bool has[4];
; #pragma unroll
;             for (int r = 0; r < 4; ++r) { const int t = tb + r * NGW; has[r] = t < SEQL; mr[r] = b * SEQL + (has[r] ? t : tb); const f32x4* xr = (const f32x4*)(X + (size_t)mr[r] * D) + lane;
; #pragma unroll
;                 for (int j = 0; j < 4; ++j) v[r][j] = xr[64 * j]; }
; #pragma unroll
;             for (int r = 0; r < 4; ++r) { float q = 0.f;
; #pragma unroll
;                 for (int j = 0; j < 4; ++j) q += (v[r][j].x * v[r][j].x + v[r][j].y * v[r][j].y) + (v[r][j].z * v[r][j].z + v[r][j].w * v[r][j].w);
;                 s[r] = q; }
.Lnorm_w32:
	s_waitcnt vmcnt(32)
	v_add_f32_e32 v16, 1.0, v16
	v_add_f32_e32 v17, 1.0, v17
	v_add_f32_e32 v18, 1.0, v18
	v_add_f32_e32 v19, 1.0, v19
	v_add_f32_e32 v20, 1.0, v20
	v_add_f32_e32 v21, 1.0, v21
	v_add_f32_e32 v22, 1.0, v22
	v_add_f32_e32 v23, 1.0, v23
	v_add_f32_e32 v24, 1.0, v24
	v_add_f32_e32 v25, 1.0, v25
	v_add_f32_e32 v26, 1.0, v26
	v_add_f32_e32 v27, 1.0, v27
	v_add_f32_e32 v28, 1.0, v28
	v_add_f32_e32 v29, 1.0, v29
	v_add_f32_e32 v30, 1.0, v30
	v_add_f32_e32 v31, 1.0, v31
	v_mul_f32_e32 v16, v0, v16
	v_mul_f32_e32 v17, v1, v17
	v_mul_f32_e32 v18, v2, v18
	v_mul_f32_e32 v19, v3, v19
	v_mul_f32_e32 v20, v4, v20
	v_mul_f32_e32 v21, v5, v21
	v_mul_f32_e32 v22, v6, v22
	v_mul_f32_e32 v23, v7, v23
	v_mul_f32_e32 v24, v8, v24
	v_mul_f32_e32 v25, v9, v25
	v_mul_f32_e32 v26, v10, v26
	v_mul_f32_e32 v27, v11, v27
	v_mul_f32_e32 v28, v12, v28
	v_mul_f32_e32 v29, v13, v29
	v_mul_f32_e32 v30, v14, v30
	v_mul_f32_e32 v31, v15, v31
	v_add_f32_e32 v48, 1.0, v48
	v_add_f32_e32 v49, 1.0, v49
	v_add_f32_e32 v50, 1.0, v50
	v_add_f32_e32 v51, 1.0, v51
	v_add_f32_e32 v52, 1.0, v52
	v_add_f32_e32 v53, 1.0, v53
	v_add_f32_e32 v54, 1.0, v54
	v_add_f32_e32 v55, 1.0, v55
	v_add_f32_e32 v56, 1.0, v56
	v_add_f32_e32 v57, 1.0, v57
	v_add_f32_e32 v58, 1.0, v58
	v_add_f32_e32 v59, 1.0, v59
	v_add_f32_e32 v60, 1.0, v60
	v_add_f32_e32 v61, 1.0, v61
	v_add_f32_e32 v62, 1.0, v62
	v_add_f32_e32 v63, 1.0, v63
	v_mul_f32_e32 v48, v0, v48
	v_mul_f32_e32 v49, v1, v49
	v_mul_f32_e32 v50, v2, v50
	v_mul_f32_e32 v51, v3, v51
	v_mul_f32_e32 v52, v4, v52
	v_mul_f32_e32 v53, v5, v53
	v_mul_f32_e32 v54, v6, v54
	v_mul_f32_e32 v55, v7, v55
	v_mul_f32_e32 v56, v8, v56
	v_mul_f32_e32 v57, v9, v57
	v_mul_f32_e32 v58, v10, v58
	v_mul_f32_e32 v59, v11, v59
	v_mul_f32_e32 v60, v12, v60
	v_mul_f32_e32 v61, v13, v61
	v_mul_f32_e32 v62, v14, v62
	v_mul_f32_e32 v63, v15, v63
	s_waitcnt vmcnt(28)
	v_mul_f32_e32 v250, v116, v116
	v_mul_f32_e32 v251, v118, v118
	v_fmac_f32_e32 v250, v117, v117
	v_fmac_f32_e32 v251, v119, v119
	v_add_f32_e32 v234, v250, v251
	v_mul_f32_e32 v250, v120, v120
	v_mul_f32_e32 v251, v122, v122
	v_fmac_f32_e32 v250, v121, v121
	v_fmac_f32_e32 v251, v123, v123
	v_add_f32_e32 v250, v250, v251
	v_add_f32_e32 v234, v234, v250
	v_mul_f32_e32 v250, v124, v124
	v_mul_f32_e32 v251, v126, v126
	v_fmac_f32_e32 v250, v125, v125
	v_fmac_f32_e32 v251, v127, v127
	v_add_f32_e32 v250, v250, v251
	v_add_f32_e32 v234, v234, v250
	v_mul_f32_e32 v250, v128, v128
	v_mul_f32_e32 v251, v130, v130
	v_fmac_f32_e32 v250, v129, v129
	v_fmac_f32_e32 v251, v131, v131
	v_add_f32_e32 v250, v250, v251
	v_add_f32_e32 v234, v234, v250
	s_waitcnt vmcnt(24)
	v_mul_f32_e32 v250, v132, v132
	v_mul_f32_e32 v251, v134, v134
	v_fmac_f32_e32 v250, v133, v133
	v_fmac_f32_e32 v251, v135, v135
	v_add_f32_e32 v235, v250, v251
	v_mul_f32_e32 v250, v136, v136
	v_mul_f32_e32 v251, v138, v138
	v_fmac_f32_e32 v250, v137, v137
	v_fmac_f32_e32 v251, v139, v139
	v_add_f32_e32 v250, v250, v251
	v_add_f32_e32 v235, v235, v250
	v_mul_f32_e32 v250, v140, v140
	v_mul_f32_e32 v251, v142, v142
	v_fmac_f32_e32 v250, v141, v141
	v_fmac_f32_e32 v251, v143, v143
	v_add_f32_e32 v250, v250, v251
	v_add_f32_e32 v235, v235, v250
	v_mul_f32_e32 v250, v144, v144
	v_mul_f32_e32 v251, v146, v146
	v_fmac_f32_e32 v250, v145, v145
	v_fmac_f32_e32 v251, v147, v147
	v_add_f32_e32 v250, v250, v251
	v_add_f32_e32 v235, v235, v250
	s_waitcnt vmcnt(20)
	v_mul_f32_e32 v250, v148, v148
	v_mul_f32_e32 v251, v150, v150
	v_fmac_f32_e32 v250, v149, v149
	v_fmac_f32_e32 v251, v151, v151
	v_add_f32_e32 v236, v250, v251
	v_mul_f32_e32 v250, v152, v152
	v_mul_f32_e32 v251, v154, v154
	v_fmac_f32_e32 v250, v153, v153
	v_fmac_f32_e32 v251, v155, v155
	v_add_f32_e32 v250, v250, v251
	v_add_f32_e32 v236, v236, v250
	v_mul_f32_e32 v250, v156, v156
	v_mul_f32_e32 v251, v158, v158
	v_fmac_f32_e32 v250, v157, v157
	v_fmac_f32_e32 v251, v159, v159
	v_add_f32_e32 v250, v250, v251
	v_add_f32_e32 v236, v236, v250
	v_mul_f32_e32 v250, v160, v160
	v_mul_f32_e32 v251, v162, v162
	v_fmac_f32_e32 v250, v161, v161
	v_fmac_f32_e32 v251, v163, v163
	v_add_f32_e32 v250, v250, v251
	v_add_f32_e32 v236, v236, v250
	s_waitcnt vmcnt(16)
	v_mul_f32_e32 v250, v164, v164
	v_mul_f32_e32 v251, v166, v166
	v_fmac_f32_e32 v250, v165, v165
	v_fmac_f32_e32 v251, v167, v167
	v_add_f32_e32 v237, v250, v251
	v_mul_f32_e32 v250, v168, v168
	v_mul_f32_e32 v251, v170, v170
	v_fmac_f32_e32 v250, v169, v169
	v_fmac_f32_e32 v251, v171, v171
	v_add_f32_e32 v250, v250, v251
	v_add_f32_e32 v237, v237, v250
	v_mul_f32_e32 v250, v172, v172
	v_mul_f32_e32 v251, v174, v174
	v_fmac_f32_e32 v250, v173, v173
	v_fmac_f32_e32 v251, v175, v175
	v_add_f32_e32 v250, v250, v251
	v_add_f32_e32 v237, v237, v250
	v_mul_f32_e32 v250, v176, v176
	v_mul_f32_e32 v251, v178, v178
	v_fmac_f32_e32 v250, v177, v177
	v_fmac_f32_e32 v251, v179, v179
	v_add_f32_e32 v250, v250, v251
	v_add_f32_e32 v237, v237, v250
	s_waitcnt vmcnt(12)
	v_mul_f32_e32 v250, v180, v180
	v_mul_f32_e32 v251, v182, v182
	v_fmac_f32_e32 v250, v181, v181
	v_fmac_f32_e32 v251, v183, v183
	v_add_f32_e32 v238, v250, v251
	v_mul_f32_e32 v250, v184, v184
	v_mul_f32_e32 v251, v186, v186
	v_fmac_f32_e32 v250, v185, v185
	v_fmac_f32_e32 v251, v187, v187
	v_add_f32_e32 v250, v250, v251
	v_add_f32_e32 v238, v238, v250
	v_mul_f32_e32 v250, v188, v188
	v_mul_f32_e32 v251, v190, v190
	v_fmac_f32_e32 v250, v189, v189
	v_fmac_f32_e32 v251, v191, v191
	v_add_f32_e32 v250, v250, v251
	v_add_f32_e32 v238, v238, v250
	v_mul_f32_e32 v250, v192, v192
	v_mul_f32_e32 v251, v194, v194
	v_fmac_f32_e32 v250, v193, v193
	v_fmac_f32_e32 v251, v195, v195
	v_add_f32_e32 v250, v250, v251
	v_add_f32_e32 v238, v238, v250
	s_waitcnt vmcnt(8)
; __device__ __forceinline__ void norm_mod_phase(const float* X, const float* ng, const float* mod, bf16* H, int G) {
;     ...
;             for (int r = 0; r < 4; ++r) { float q = 0.f;
; #pragma unroll
;                 for (int j = 0; j < 4; ++j) q += (v[r][j].x * v[r][j].x + v[r][j].y * v[r][j].y) + (v[r][j].z * v[r][j].z + v[r][j].w * v[r][j].w);
;                 s[r] = q; }
; #pragma unroll
;             for (int o = 1; o < 64; o <<= 1) {
; #pragma unroll
;                 for (int r = 0; r < 4; ++r) s[r] += __shfl_xor(s[r], o); }
	v_mul_f32_e32 v250, v86, v86
	v_mul_f32_e32 v251, v88, v88
	v_fmac_f32_e32 v250, v87, v87
	v_fmac_f32_e32 v251, v89, v89
	v_add_f32_e32 v239, v250, v251
	v_mul_f32_e32 v250, v90, v90
	v_mul_f32_e32 v251, v92, v92
	v_fmac_f32_e32 v250, v91, v91
	v_fmac_f32_e32 v251, v93, v93
	v_add_f32_e32 v250, v250, v251
	v_add_f32_e32 v239, v239, v250
	v_mul_f32_e32 v250, v94, v94
	v_mul_f32_e32 v251, v96, v96
	v_fmac_f32_e32 v250, v95, v95
	v_fmac_f32_e32 v251, v97, v97
	v_add_f32_e32 v250, v250, v251
	v_add_f32_e32 v239, v239, v250
	v_mul_f32_e32 v250, v98, v98
	v_mul_f32_e32 v251, v100, v100
	v_fmac_f32_e32 v250, v99, v99
	v_fmac_f32_e32 v251, v101, v101
	v_add_f32_e32 v250, v250, v251
	v_add_f32_e32 v239, v239, v250
	s_waitcnt vmcnt(4)
	v_mul_f32_e32 v250, v218, v218
	v_mul_f32_e32 v251, v220, v220
	v_fmac_f32_e32 v250, v219, v219
	v_fmac_f32_e32 v251, v221, v221
	v_add_f32_e32 v240, v250, v251
	v_mul_f32_e32 v250, v222, v222
	v_mul_f32_e32 v251, v224, v224
	v_fmac_f32_e32 v250, v223, v223
	v_fmac_f32_e32 v251, v225, v225
	v_add_f32_e32 v250, v250, v251
	v_add_f32_e32 v240, v240, v250
	v_mul_f32_e32 v250, v226, v226
	v_mul_f32_e32 v251, v228, v228
	v_fmac_f32_e32 v250, v227, v227
	v_fmac_f32_e32 v251, v229, v229
	v_add_f32_e32 v250, v250, v251
	v_add_f32_e32 v240, v240, v250
	v_mul_f32_e32 v250, v230, v230
	v_mul_f32_e32 v251, v232, v232
	v_fmac_f32_e32 v250, v231, v231
	v_fmac_f32_e32 v251, v233, v233
	v_add_f32_e32 v250, v250, v251
	v_add_f32_e32 v240, v240, v250
	s_waitcnt vmcnt(0)
	v_mul_f32_e32 v250, v196, v196
	v_mul_f32_e32 v251, v198, v198
	v_fmac_f32_e32 v250, v197, v197
	v_fmac_f32_e32 v251, v199, v199
	v_add_f32_e32 v241, v250, v251
	v_mul_f32_e32 v250, v200, v200
	v_mul_f32_e32 v251, v202, v202
	v_fmac_f32_e32 v250, v201, v201
	v_fmac_f32_e32 v251, v203, v203
	v_add_f32_e32 v250, v250, v251
	v_add_f32_e32 v241, v241, v250
	v_mul_f32_e32 v250, v204, v204
	v_mul_f32_e32 v251, v206, v206
	v_fmac_f32_e32 v250, v205, v205
	v_fmac_f32_e32 v251, v207, v207
	v_add_f32_e32 v250, v250, v251
	v_add_f32_e32 v241, v241, v250
	v_mul_f32_e32 v250, v102, v102
	v_mul_f32_e32 v251, v104, v104
	v_fmac_f32_e32 v250, v103, v103
	v_fmac_f32_e32 v251, v105, v105
	v_add_f32_e32 v250, v250, v251
	v_add_f32_e32 v241, v241, v250
	ds_bpermute_b32 v109, v242, v234
	ds_bpermute_b32 v110, v242, v235
	ds_bpermute_b32 v111, v242, v236
	ds_bpermute_b32 v112, v242, v237
	ds_bpermute_b32 v113, v242, v238
	ds_bpermute_b32 v114, v242, v239
	ds_bpermute_b32 v252, v242, v240
	ds_bpermute_b32 v253, v242, v241
	s_waitcnt lgkmcnt(7)
	v_add_f32_e32 v234, v234, v109
	s_waitcnt lgkmcnt(6)
	v_add_f32_e32 v235, v235, v110
	s_waitcnt lgkmcnt(5)
	v_add_f32_e32 v236, v236, v111
	s_waitcnt lgkmcnt(4)
	v_add_f32_e32 v237, v237, v112
	s_waitcnt lgkmcnt(3)
	v_add_f32_e32 v238, v238, v113
	s_waitcnt lgkmcnt(2)
	v_add_f32_e32 v239, v239, v114
	s_waitcnt lgkmcnt(1)
	v_add_f32_e32 v240, v240, v252
	s_waitcnt lgkmcnt(0)
	v_add_f32_e32 v241, v241, v253
	ds_bpermute_b32 v109, v243, v234
	ds_bpermute_b32 v110, v243, v235
	ds_bpermute_b32 v111, v243, v236
	ds_bpermute_b32 v112, v243, v237
	ds_bpermute_b32 v113, v243, v238
	ds_bpermute_b32 v114, v243, v239
	ds_bpermute_b32 v252, v243, v240
	ds_bpermute_b32 v253, v243, v241
	s_waitcnt lgkmcnt(7)
	v_add_f32_e32 v234, v234, v109
	s_waitcnt lgkmcnt(6)
	v_add_f32_e32 v235, v235, v110
	s_waitcnt lgkmcnt(5)
	v_add_f32_e32 v236, v236, v111
	s_waitcnt lgkmcnt(4)
	v_add_f32_e32 v237, v237, v112
	s_waitcnt lgkmcnt(3)
	v_add_f32_e32 v238, v238, v113
	s_waitcnt lgkmcnt(2)
	v_add_f32_e32 v239, v239, v114
	s_waitcnt lgkmcnt(1)
	v_add_f32_e32 v240, v240, v252
	s_waitcnt lgkmcnt(0)
	v_add_f32_e32 v241, v241, v253
	ds_bpermute_b32 v109, v244, v234
	ds_bpermute_b32 v110, v244, v235
	ds_bpermute_b32 v111, v244, v236
	ds_bpermute_b32 v112, v244, v237
	ds_bpermute_b32 v113, v244, v238
	ds_bpermute_b32 v114, v244, v239
	ds_bpermute_b32 v252, v244, v240
	ds_bpermute_b32 v253, v244, v241
	s_waitcnt lgkmcnt(7)
	v_add_f32_e32 v234, v234, v109
	s_waitcnt lgkmcnt(6)
	v_add_f32_e32 v235, v235, v110
	s_waitcnt lgkmcnt(5)
	v_add_f32_e32 v236, v236, v111
	s_waitcnt lgkmcnt(4)
	v_add_f32_e32 v237, v237, v112
	s_waitcnt lgkmcnt(3)
	v_add_f32_e32 v238, v238, v113
	s_waitcnt lgkmcnt(2)
	v_add_f32_e32 v239, v239, v114
	s_waitcnt lgkmcnt(1)
	v_add_f32_e32 v240, v240, v252
	s_waitcnt lgkmcnt(0)
	v_add_f32_e32 v241, v241, v253
	ds_bpermute_b32 v109, v245, v234
	ds_bpermute_b32 v110, v245, v235
	ds_bpermute_b32 v111, v245, v236
	ds_bpermute_b32 v112, v245, v237
	ds_bpermute_b32 v113, v245, v238
	ds_bpermute_b32 v114, v245, v239
	ds_bpermute_b32 v252, v245, v240
	ds_bpermute_b32 v253, v245, v241
	s_waitcnt lgkmcnt(7)
	v_add_f32_e32 v234, v234, v109
	s_waitcnt lgkmcnt(6)
	v_add_f32_e32 v235, v235, v110
	s_waitcnt lgkmcnt(5)
	v_add_f32_e32 v236, v236, v111
	s_waitcnt lgkmcnt(4)
	v_add_f32_e32 v237, v237, v112
	s_waitcnt lgkmcnt(3)
	v_add_f32_e32 v238, v238, v113
	s_waitcnt lgkmcnt(2)
	v_add_f32_e32 v239, v239, v114
	s_waitcnt lgkmcnt(1)
	v_add_f32_e32 v240, v240, v252
	s_waitcnt lgkmcnt(0)
	v_add_f32_e32 v241, v241, v253
	ds_bpermute_b32 v109, v246, v234
	ds_bpermute_b32 v110, v246, v235
	ds_bpermute_b32 v111, v246, v236
	ds_bpermute_b32 v112, v246, v237
	ds_bpermute_b32 v113, v246, v238
	ds_bpermute_b32 v114, v246, v239
	ds_bpermute_b32 v252, v246, v240
	ds_bpermute_b32 v253, v246, v241
	s_waitcnt lgkmcnt(7)
	v_add_f32_e32 v234, v234, v109
	s_waitcnt lgkmcnt(6)
	v_add_f32_e32 v235, v235, v110
	s_waitcnt lgkmcnt(5)
	v_add_f32_e32 v236, v236, v111
	s_waitcnt lgkmcnt(4)
	v_add_f32_e32 v237, v237, v112
	s_waitcnt lgkmcnt(3)
	v_add_f32_e32 v238, v238, v113
	s_waitcnt lgkmcnt(2)
; __device__ __forceinline__ unsigned pk2(float lo, float hi) { f32x2_t v = {lo, hi}; bf16x2_t b = __builtin_convertvector(v, bf16x2_t); return __builtin_bit_cast(unsigned, b); }
; __device__ __forceinline__ void norm_mod_phase(const float* X, const float* ng, const float* mod, bf16* H, int G) {
;     ...
;             for (int o = 1; o < 64; o <<= 1) {
; #pragma unroll
;                 for (int r = 0; r < 4; ++r) s[r] += __shfl_xor(s[r], o); }
; #pragma unroll
;             for (int r = 0; r < 4; ++r) { if (!has[r]) continue;
;                 const float rs = __builtin_amdgcn_rsqf(s[r] * (1.f / D) + EPSN); v2u* o8 = (v2u*)(H + (size_t)mr[r] * D) + lane;
; #pragma unroll
;                 for (int j = 0; j < 4; ++j) { const f32x4 h = v[r][j] * rs * gs[j] + sh[j]; o8[64 * j] = (v2u){pk2(h.x, h.y), pk2(h.z, h.w)}; } }
	v_add_f32_e32 v239, v239, v114
	s_waitcnt lgkmcnt(1)
	v_add_f32_e32 v240, v240, v252
	s_waitcnt lgkmcnt(0)
	v_add_f32_e32 v241, v241, v253
	ds_bpermute_b32 v109, v247, v234
	ds_bpermute_b32 v110, v247, v235
	ds_bpermute_b32 v111, v247, v236
	ds_bpermute_b32 v112, v247, v237
	ds_bpermute_b32 v113, v247, v238
	ds_bpermute_b32 v114, v247, v239
	ds_bpermute_b32 v252, v247, v240
	ds_bpermute_b32 v253, v247, v241
	s_waitcnt lgkmcnt(7)
	v_add_f32_e32 v234, v234, v109
	s_waitcnt lgkmcnt(6)
	v_add_f32_e32 v235, v235, v110
	s_waitcnt lgkmcnt(5)
	v_add_f32_e32 v236, v236, v111
	s_waitcnt lgkmcnt(4)
	v_add_f32_e32 v237, v237, v112
	s_waitcnt lgkmcnt(3)
	v_add_f32_e32 v238, v238, v113
	s_waitcnt lgkmcnt(2)
	v_add_f32_e32 v239, v239, v114
	s_waitcnt lgkmcnt(1)
	v_add_f32_e32 v240, v240, v252
	s_waitcnt lgkmcnt(0)
	v_add_f32_e32 v241, v241, v253
	v_fmamk_f32 v234, v234, 0x3a800000, v108
	v_fmamk_f32 v235, v235, 0x3a800000, v108
	v_fmamk_f32 v236, v236, 0x3a800000, v108
	v_fmamk_f32 v237, v237, 0x3a800000, v108
	v_fmamk_f32 v238, v238, 0x3a800000, v108
	v_fmamk_f32 v239, v239, 0x3a800000, v108
	v_fmamk_f32 v240, v240, 0x3a800000, v108
	v_fmamk_f32 v241, v241, 0x3a800000, v108
	v_rsq_f32_e32 v234, v234
	v_rsq_f32_e32 v235, v235
	v_rsq_f32_e32 v236, v236
	v_rsq_f32_e32 v237, v237
	v_rsq_f32_e32 v238, v238
	v_rsq_f32_e32 v239, v239
	v_rsq_f32_e32 v240, v240
	v_rsq_f32_e32 v241, v241
	s_nop 0
	s_mov_b32 s18, s16
	s_lshl_b32 s20, s18, 11
	s_add_u32 s22, s12, s20
	s_addc_u32 s23, s13, 0
	v_mul_f32_e32 v116, v116, v234
	v_mul_f32_e32 v117, v117, v234
	v_mul_f32_e32 v118, v118, v234
	v_mul_f32_e32 v119, v119, v234
	v_fma_f32 v116, v116, v16, v32
	v_fma_f32 v117, v117, v17, v33
	v_fma_f32 v118, v118, v18, v34
	v_fma_f32 v119, v119, v19, v35
	v_cvt_pk_bf16_f32 v116, v116, v117
	v_cvt_pk_bf16_f32 v117, v118, v119
	global_store_dwordx2 v106, v[116:117], s[22:23]
	v_mul_f32_e32 v120, v120, v234
	v_mul_f32_e32 v121, v121, v234
	v_mul_f32_e32 v122, v122, v234
	v_mul_f32_e32 v123, v123, v234
	v_fma_f32 v120, v120, v20, v36
	v_fma_f32 v121, v121, v21, v37
	v_fma_f32 v122, v122, v22, v38
	v_fma_f32 v123, v123, v23, v39
	v_cvt_pk_bf16_f32 v120, v120, v121
	v_cvt_pk_bf16_f32 v121, v122, v123
	global_store_dwordx2 v106, v[120:121], s[22:23] offset:512
	v_mul_f32_e32 v124, v124, v234
	v_mul_f32_e32 v125, v125, v234
	v_mul_f32_e32 v126, v126, v234
	v_mul_f32_e32 v127, v127, v234
	v_fma_f32 v124, v124, v24, v40
	v_fma_f32 v125, v125, v25, v41
	v_fma_f32 v126, v126, v26, v42
	v_fma_f32 v127, v127, v27, v43
	v_cvt_pk_bf16_f32 v124, v124, v125
	v_cvt_pk_bf16_f32 v125, v126, v127
	global_store_dwordx2 v106, v[124:125], s[22:23] offset:1024
	v_mul_f32_e32 v128, v128, v234
	v_mul_f32_e32 v129, v129, v234
	v_mul_f32_e32 v130, v130, v234
	v_mul_f32_e32 v131, v131, v234
	v_fma_f32 v128, v128, v28, v44
	v_fma_f32 v129, v129, v29, v45
	v_fma_f32 v130, v130, v30, v46
	v_fma_f32 v131, v131, v31, v47
	v_cvt_pk_bf16_f32 v128, v128, v129
	v_cvt_pk_bf16_f32 v129, v130, v131
	global_store_dwordx2 v106, v[128:129], s[22:23] offset:1536
	s_add_i32 s18, s18, s14
	s_lshl_b32 s20, s18, 11
	s_add_u32 s22, s12, s20
	s_addc_u32 s23, s13, 0
	v_mul_f32_e32 v132, v132, v235
	v_mul_f32_e32 v133, v133, v235
	v_mul_f32_e32 v134, v134, v235
	v_mul_f32_e32 v135, v135, v235
	v_fma_f32 v132, v132, v16, v32
	v_fma_f32 v133, v133, v17, v33
	v_fma_f32 v134, v134, v18, v34
	v_fma_f32 v135, v135, v19, v35
	v_cvt_pk_bf16_f32 v132, v132, v133
	v_cvt_pk_bf16_f32 v133, v134, v135
	global_store_dwordx2 v106, v[132:133], s[22:23]
	v_mul_f32_e32 v136, v136, v235
	v_mul_f32_e32 v137, v137, v235
	v_mul_f32_e32 v138, v138, v235
	v_mul_f32_e32 v139, v139, v235
	v_fma_f32 v136, v136, v20, v36
	v_fma_f32 v137, v137, v21, v37
	v_fma_f32 v138, v138, v22, v38
	v_fma_f32 v139, v139, v23, v39
	v_cvt_pk_bf16_f32 v136, v136, v137
	v_cvt_pk_bf16_f32 v137, v138, v139
	global_store_dwordx2 v106, v[136:137], s[22:23] offset:512
	v_mul_f32_e32 v140, v140, v235
	v_mul_f32_e32 v141, v141, v235
	v_mul_f32_e32 v142, v142, v235
	v_mul_f32_e32 v143, v143, v235
	v_fma_f32 v140, v140, v24, v40
	v_fma_f32 v141, v141, v25, v41
	v_fma_f32 v142, v142, v26, v42
	v_fma_f32 v143, v143, v27, v43
	v_cvt_pk_bf16_f32 v140, v140, v141
	v_cvt_pk_bf16_f32 v141, v142, v143
	global_store_dwordx2 v106, v[140:141], s[22:23] offset:1024
	v_mul_f32_e32 v144, v144, v235
	v_mul_f32_e32 v145, v145, v235
	v_mul_f32_e32 v146, v146, v235
	v_mul_f32_e32 v147, v147, v235
	v_fma_f32 v144, v144, v28, v44
	v_fma_f32 v145, v145, v29, v45
	v_fma_f32 v146, v146, v30, v46
	v_fma_f32 v147, v147, v31, v47
	v_cvt_pk_bf16_f32 v144, v144, v145
	v_cvt_pk_bf16_f32 v145, v146, v147
	global_store_dwordx2 v106, v[144:145], s[22:23] offset:1536
	s_add_i32 s18, s18, s14
	s_lshl_b32 s20, s18, 11
	s_add_u32 s22, s12, s20
	s_addc_u32 s23, s13, 0
	v_mul_f32_e32 v148, v148, v236
	v_mul_f32_e32 v149, v149, v236
	v_mul_f32_e32 v150, v150, v236
	v_mul_f32_e32 v151, v151, v236
	v_fma_f32 v148, v148, v16, v32
	v_fma_f32 v149, v149, v17, v33
	v_fma_f32 v150, v150, v18, v34
	v_fma_f32 v151, v151, v19, v35
	v_cvt_pk_bf16_f32 v148, v148, v149
	v_cvt_pk_bf16_f32 v149, v150, v151
	global_store_dwordx2 v106, v[148:149], s[22:23]
	v_mul_f32_e32 v152, v152, v236
	v_mul_f32_e32 v153, v153, v236
	v_mul_f32_e32 v154, v154, v236
	v_mul_f32_e32 v155, v155, v236
	v_fma_f32 v152, v152, v20, v36
	v_fma_f32 v153, v153, v21, v37
	v_fma_f32 v154, v154, v22, v38
	v_fma_f32 v155, v155, v23, v39
	v_cvt_pk_bf16_f32 v152, v152, v153
	v_cvt_pk_bf16_f32 v153, v154, v155
	global_store_dwordx2 v106, v[152:153], s[22:23] offset:512
	v_mul_f32_e32 v156, v156, v236
	v_mul_f32_e32 v157, v157, v236
	v_mul_f32_e32 v158, v158, v236
; __device__ __forceinline__ unsigned pk2(float lo, float hi) { f32x2_t v = {lo, hi}; bf16x2_t b = __builtin_convertvector(v, bf16x2_t); return __builtin_bit_cast(unsigned, b); }
; __device__ __forceinline__ void norm_mod_phase(const float* X, const float* ng, const float* mod, bf16* H, int G) {
;     ...
;             for (int r = 0; r < 4; ++r) { if (!has[r]) continue;
;                 const float rs = __builtin_amdgcn_rsqf(s[r] * (1.f / D) + EPSN); v2u* o8 = (v2u*)(H + (size_t)mr[r] * D) + lane;
; #pragma unroll
;                 for (int j = 0; j < 4; ++j) { const f32x4 h = v[r][j] * rs * gs[j] + sh[j]; o8[64 * j] = (v2u){pk2(h.x, h.y), pk2(h.z, h.w)}; } }
	v_mul_f32_e32 v159, v159, v236
	v_fma_f32 v156, v156, v24, v40
	v_fma_f32 v157, v157, v25, v41
	v_fma_f32 v158, v158, v26, v42
	v_fma_f32 v159, v159, v27, v43
	v_cvt_pk_bf16_f32 v156, v156, v157
	v_cvt_pk_bf16_f32 v157, v158, v159
	global_store_dwordx2 v106, v[156:157], s[22:23] offset:1024
	v_mul_f32_e32 v160, v160, v236
	v_mul_f32_e32 v161, v161, v236
	v_mul_f32_e32 v162, v162, v236
	v_mul_f32_e32 v163, v163, v236
	v_fma_f32 v160, v160, v28, v44
	v_fma_f32 v161, v161, v29, v45
	v_fma_f32 v162, v162, v30, v46
	v_fma_f32 v163, v163, v31, v47
	v_cvt_pk_bf16_f32 v160, v160, v161
	v_cvt_pk_bf16_f32 v161, v162, v163
	global_store_dwordx2 v106, v[160:161], s[22:23] offset:1536
	s_add_i32 s18, s18, s14
	s_lshl_b32 s20, s18, 11
	s_add_u32 s22, s12, s20
	s_addc_u32 s23, s13, 0
	v_mul_f32_e32 v164, v164, v237
	v_mul_f32_e32 v165, v165, v237
	v_mul_f32_e32 v166, v166, v237
	v_mul_f32_e32 v167, v167, v237
	v_fma_f32 v164, v164, v16, v32
	v_fma_f32 v165, v165, v17, v33
	v_fma_f32 v166, v166, v18, v34
	v_fma_f32 v167, v167, v19, v35
	v_cvt_pk_bf16_f32 v164, v164, v165
	v_cvt_pk_bf16_f32 v165, v166, v167
	global_store_dwordx2 v106, v[164:165], s[22:23]
	v_mul_f32_e32 v168, v168, v237
	v_mul_f32_e32 v169, v169, v237
	v_mul_f32_e32 v170, v170, v237
	v_mul_f32_e32 v171, v171, v237
	v_fma_f32 v168, v168, v20, v36
	v_fma_f32 v169, v169, v21, v37
	v_fma_f32 v170, v170, v22, v38
	v_fma_f32 v171, v171, v23, v39
	v_cvt_pk_bf16_f32 v168, v168, v169
	v_cvt_pk_bf16_f32 v169, v170, v171
	global_store_dwordx2 v106, v[168:169], s[22:23] offset:512
	v_mul_f32_e32 v172, v172, v237
	v_mul_f32_e32 v173, v173, v237
	v_mul_f32_e32 v174, v174, v237
	v_mul_f32_e32 v175, v175, v237
	v_fma_f32 v172, v172, v24, v40
	v_fma_f32 v173, v173, v25, v41
	v_fma_f32 v174, v174, v26, v42
	v_fma_f32 v175, v175, v27, v43
	v_cvt_pk_bf16_f32 v172, v172, v173
	v_cvt_pk_bf16_f32 v173, v174, v175
	global_store_dwordx2 v106, v[172:173], s[22:23] offset:1024
	v_mul_f32_e32 v176, v176, v237
	v_mul_f32_e32 v177, v177, v237
	v_mul_f32_e32 v178, v178, v237
	v_mul_f32_e32 v179, v179, v237
	v_fma_f32 v176, v176, v28, v44
	v_fma_f32 v177, v177, v29, v45
	v_fma_f32 v178, v178, v30, v46
	v_fma_f32 v179, v179, v31, v47
	v_cvt_pk_bf16_f32 v176, v176, v177
	v_cvt_pk_bf16_f32 v177, v178, v179
	global_store_dwordx2 v106, v[176:177], s[22:23] offset:1536
	s_add_i32 s18, s16, 8192
	s_lshl_b32 s20, s18, 11
	s_add_u32 s22, s12, s20
	s_addc_u32 s23, s13, 0
	v_mul_f32_e32 v180, v180, v238
	v_mul_f32_e32 v181, v181, v238
	v_mul_f32_e32 v182, v182, v238
	v_mul_f32_e32 v183, v183, v238
	v_fma_f32 v180, v180, v48, v64
	v_fma_f32 v181, v181, v49, v65
	v_fma_f32 v182, v182, v50, v66
	v_fma_f32 v183, v183, v51, v67
	v_cvt_pk_bf16_f32 v180, v180, v181
	v_cvt_pk_bf16_f32 v181, v182, v183
	global_store_dwordx2 v106, v[180:181], s[22:23]
	v_mul_f32_e32 v184, v184, v238
	v_mul_f32_e32 v185, v185, v238
	v_mul_f32_e32 v186, v186, v238
	v_mul_f32_e32 v187, v187, v238
	v_fma_f32 v184, v184, v52, v68
	v_fma_f32 v185, v185, v53, v69
	v_fma_f32 v186, v186, v54, v70
	v_fma_f32 v187, v187, v55, v71
	v_cvt_pk_bf16_f32 v184, v184, v185
	v_cvt_pk_bf16_f32 v185, v186, v187
	global_store_dwordx2 v106, v[184:185], s[22:23] offset:512
	v_mul_f32_e32 v188, v188, v238
	v_mul_f32_e32 v189, v189, v238
	v_mul_f32_e32 v190, v190, v238
	v_mul_f32_e32 v191, v191, v238
	v_fma_f32 v188, v188, v56, v72
	v_fma_f32 v189, v189, v57, v73
	v_fma_f32 v190, v190, v58, v74
	v_fma_f32 v191, v191, v59, v75
	v_cvt_pk_bf16_f32 v188, v188, v189
	v_cvt_pk_bf16_f32 v189, v190, v191
	global_store_dwordx2 v106, v[188:189], s[22:23] offset:1024
	v_mul_f32_e32 v192, v192, v238
	v_mul_f32_e32 v193, v193, v238
	v_mul_f32_e32 v194, v194, v238
	v_mul_f32_e32 v195, v195, v238
	v_fma_f32 v192, v192, v60, v76
	v_fma_f32 v193, v193, v61, v77
	v_fma_f32 v194, v194, v62, v78
	v_fma_f32 v195, v195, v63, v79
	v_cvt_pk_bf16_f32 v192, v192, v193
	v_cvt_pk_bf16_f32 v193, v194, v195
	global_store_dwordx2 v106, v[192:193], s[22:23] offset:1536
	s_add_i32 s18, s18, s14
	s_lshl_b32 s20, s18, 11
	s_add_u32 s22, s12, s20
	s_addc_u32 s23, s13, 0
	v_mul_f32_e32 v86, v86, v239
	v_mul_f32_e32 v87, v87, v239
	v_mul_f32_e32 v88, v88, v239
	v_mul_f32_e32 v89, v89, v239
	v_fma_f32 v86, v86, v48, v64
	v_fma_f32 v87, v87, v49, v65
	v_fma_f32 v88, v88, v50, v66
	v_fma_f32 v89, v89, v51, v67
	v_cvt_pk_bf16_f32 v86, v86, v87
	v_cvt_pk_bf16_f32 v87, v88, v89
	global_store_dwordx2 v106, v[86:87], s[22:23]
; __device__ __forceinline__ unsigned pk2(float lo, float hi) { f32x2_t v = {lo, hi}; bf16x2_t b = __builtin_convertvector(v, bf16x2_t); return __builtin_bit_cast(unsigned, b); }
; __device__ __forceinline__ void norm_mod_phase(const float* X, const float* ng, const float* mod, bf16* H, int G) {
;     ...
;             for (int r = 0; r < 4; ++r) { if (!has[r]) continue;
;                 const float rs = __builtin_amdgcn_rsqf(s[r] * (1.f / D) + EPSN); v2u* o8 = (v2u*)(H + (size_t)mr[r] * D) + lane;
; #pragma unroll
;                 for (int j = 0; j < 4; ++j) { const f32x4 h = v[r][j] * rs * gs[j] + sh[j]; o8[64 * j] = (v2u){pk2(h.x, h.y), pk2(h.z, h.w)}; } }
	v_mul_f32_e32 v90, v90, v239
	v_mul_f32_e32 v91, v91, v239
	v_mul_f32_e32 v92, v92, v239
	v_mul_f32_e32 v93, v93, v239
	v_fma_f32 v90, v90, v52, v68
	v_fma_f32 v91, v91, v53, v69
	v_fma_f32 v92, v92, v54, v70
	v_fma_f32 v93, v93, v55, v71
	v_cvt_pk_bf16_f32 v90, v90, v91
	v_cvt_pk_bf16_f32 v91, v92, v93
	global_store_dwordx2 v106, v[90:91], s[22:23] offset:512
	v_mul_f32_e32 v94, v94, v239
	v_mul_f32_e32 v95, v95, v239
	v_mul_f32_e32 v96, v96, v239
	v_mul_f32_e32 v97, v97, v239
	v_fma_f32 v94, v94, v56, v72
	v_fma_f32 v95, v95, v57, v73
	v_fma_f32 v96, v96, v58, v74
	v_fma_f32 v97, v97, v59, v75
	v_cvt_pk_bf16_f32 v94, v94, v95
	v_cvt_pk_bf16_f32 v95, v96, v97
	global_store_dwordx2 v106, v[94:95], s[22:23] offset:1024
	v_mul_f32_e32 v98, v98, v239
	v_mul_f32_e32 v99, v99, v239
	v_mul_f32_e32 v100, v100, v239
	v_mul_f32_e32 v101, v101, v239
	v_fma_f32 v98, v98, v60, v76
	v_fma_f32 v99, v99, v61, v77
	v_fma_f32 v100, v100, v62, v78
	v_fma_f32 v101, v101, v63, v79
	v_cvt_pk_bf16_f32 v98, v98, v99
	v_cvt_pk_bf16_f32 v99, v100, v101
	global_store_dwordx2 v106, v[98:99], s[22:23] offset:1536
	s_add_i32 s18, s18, s14
	s_lshl_b32 s20, s18, 11
	s_add_u32 s22, s12, s20
	s_addc_u32 s23, s13, 0
	v_mul_f32_e32 v218, v218, v240
	v_mul_f32_e32 v219, v219, v240
	v_mul_f32_e32 v220, v220, v240
	v_mul_f32_e32 v221, v221, v240
	v_fma_f32 v218, v218, v48, v64
	v_fma_f32 v219, v219, v49, v65
	v_fma_f32 v220, v220, v50, v66
	v_fma_f32 v221, v221, v51, v67
	v_cvt_pk_bf16_f32 v218, v218, v219
	v_cvt_pk_bf16_f32 v219, v220, v221
	global_store_dwordx2 v106, v[218:219], s[22:23]
	v_mul_f32_e32 v222, v222, v240
	v_mul_f32_e32 v223, v223, v240
	v_mul_f32_e32 v224, v224, v240
	v_mul_f32_e32 v225, v225, v240
	v_fma_f32 v222, v222, v52, v68
	v_fma_f32 v223, v223, v53, v69
	v_fma_f32 v224, v224, v54, v70
	v_fma_f32 v225, v225, v55, v71
	v_cvt_pk_bf16_f32 v222, v222, v223
	v_cvt_pk_bf16_f32 v223, v224, v225
	global_store_dwordx2 v106, v[222:223], s[22:23] offset:512
	v_mul_f32_e32 v226, v226, v240
	v_mul_f32_e32 v227, v227, v240
	v_mul_f32_e32 v228, v228, v240
	v_mul_f32_e32 v229, v229, v240
	v_fma_f32 v226, v226, v56, v72
	v_fma_f32 v227, v227, v57, v73
	v_fma_f32 v228, v228, v58, v74
	v_fma_f32 v229, v229, v59, v75
	v_cvt_pk_bf16_f32 v226, v226, v227
	v_cvt_pk_bf16_f32 v227, v228, v229
	global_store_dwordx2 v106, v[226:227], s[22:23] offset:1024
	v_mul_f32_e32 v230, v230, v240
	v_mul_f32_e32 v231, v231, v240
	v_mul_f32_e32 v232, v232, v240
	v_mul_f32_e32 v233, v233, v240
	v_fma_f32 v230, v230, v60, v76
	v_fma_f32 v231, v231, v61, v77
	v_fma_f32 v232, v232, v62, v78
	v_fma_f32 v233, v233, v63, v79
	v_cvt_pk_bf16_f32 v230, v230, v231
	v_cvt_pk_bf16_f32 v231, v232, v233
	global_store_dwordx2 v106, v[230:231], s[22:23] offset:1536
	s_add_i32 s18, s18, s14
	s_lshl_b32 s20, s18, 11
	s_add_u32 s22, s12, s20
	s_addc_u32 s23, s13, 0
	v_mul_f32_e32 v196, v196, v241
	v_mul_f32_e32 v197, v197, v241
	v_mul_f32_e32 v198, v198, v241
	v_mul_f32_e32 v199, v199, v241
	v_fma_f32 v196, v196, v48, v64
	v_fma_f32 v197, v197, v49, v65
	v_fma_f32 v198, v198, v50, v66
	v_fma_f32 v199, v199, v51, v67
	v_cvt_pk_bf16_f32 v196, v196, v197
	v_cvt_pk_bf16_f32 v197, v198, v199
	global_store_dwordx2 v106, v[196:197], s[22:23]
	v_mul_f32_e32 v200, v200, v241
	v_mul_f32_e32 v201, v201, v241
	v_mul_f32_e32 v202, v202, v241
	v_mul_f32_e32 v203, v203, v241
	v_fma_f32 v200, v200, v52, v68
	v_fma_f32 v201, v201, v53, v69
	v_fma_f32 v202, v202, v54, v70
	v_fma_f32 v203, v203, v55, v71
	v_cvt_pk_bf16_f32 v200, v200, v201
	v_cvt_pk_bf16_f32 v201, v202, v203
	global_store_dwordx2 v106, v[200:201], s[22:23] offset:512
	v_mul_f32_e32 v204, v204, v241
	v_mul_f32_e32 v205, v205, v241
	v_mul_f32_e32 v206, v206, v241
	v_mul_f32_e32 v207, v207, v241
	v_fma_f32 v204, v204, v56, v72
	v_fma_f32 v205, v205, v57, v73
	v_fma_f32 v206, v206, v58, v74
	v_fma_f32 v207, v207, v59, v75
	v_cvt_pk_bf16_f32 v204, v204, v205
	v_cvt_pk_bf16_f32 v205, v206, v207
	global_store_dwordx2 v106, v[204:205], s[22:23] offset:1024
	v_mul_f32_e32 v102, v102, v241
	v_mul_f32_e32 v103, v103, v241
	v_mul_f32_e32 v104, v104, v241
	v_mul_f32_e32 v105, v105, v241
	v_fma_f32 v102, v102, v60, v76
	v_fma_f32 v103, v103, v61, v77
	v_fma_f32 v104, v104, v62, v78
	v_fma_f32 v105, v105, v63, v79
	v_cvt_pk_bf16_f32 v102, v102, v103
	v_cvt_pk_bf16_f32 v103, v104, v105
	global_store_dwordx2 v106, v[102:103], s[22:23] offset:1536
	s_branch .LBB0_96
